# context-attention unit: head wait no longer drains the tile-2 DMAs, tail waits only for loads before the gating barrier
# speedup vs baseline: 1.0099x; 1.0019x over previous
; #define DMA(t) do { const int t_ = (t) < NT ? (t) : NT - 1; const long off_ = (long)t_ * (KVBLK * LDK); \
;         __builtin_amdgcn_global_load_lds((const unsigned*)(kptr + off_), (LAS unsigned*)(ldsK + SLOT(t)), 16, 0, 0); \
;         __builtin_amdgcn_global_load_lds((const unsigned*)(vptr + off_), (LAS unsigned*)(ldsV + SLOT(t)), 16, 0, 0); } while (0)
; #define WBAR(N) asm volatile("s_waitcnt vmcnt(" #N ") lgkmcnt(0)\n\ts_barrier" ::: "memory")
; #define HALF(PX0, PX1, PY0, PY1, j_, MORE) do { \
;         SBAR(); if (MORE) DMA((j_) + 2); qkt(PX0, PX1, K_lds + SLOT(j_), qr, negm, r32, hi); \
;         finishSM(PY0, PY1, l_reg, pa0, pa1, pa2, pa3); \
;         pv_d0(o, vb0 + SLOT((j_) - 1), pa0, pa1, pa2, pa3); partialSM(PX0); \
;         if (MORE) WBAR(2); else WBAR(0); } while (0)
; __device__ __forceinline__ void attn_body(const bf16* __restrict__ Qb, const bf16* __restrict__ Kh, const bf16* __restrict__ Vh, bf16* __restrict__ Ob, int seq, float m0l2, char* lds, bool pre, bool post) {
;     ...
;     f32x16 pA0, pA1, pB0, pB1; bf16x8 pa0, pa1, pa2, pa3;
;     ...
;     if (!pre) { DMA(0); DMA(1); } DMA(2); WBAR(2);
;     qkt(pA0, pA1, K_lds, qr, negm, r32, hi); partialSM(pA0);
;     int j = 1;
;     for (; j + 4 < NT; j += 2) {
;         HALF(pB0, pB1, pA0, pA1, j, true);
.LBB0_35:
	v_and_b32_e32 v18, 0x3fffffc0, v114
	s_add_i32 s6, 0, 0x10000
	v_lshl_add_u32 v113, v18, 2, s6
	v_lshlrev_b32_e32 v18, 1, v115
	v_and_b32_e32 v18, 32, v18
	s_movk_i32 s6, 0xc0
	v_and_or_b32 v16, v16, s6, v18
	v_lshlrev_b32_e32 v18, 5, v115
	v_and_b32_e32 v18, 0x400, v18
	s_add_i32 s3, s3, 0
	v_or3_b32 v119, v16, v18, v17
	v_lshl_add_u64 v[16:17], v[48:49], 0, s[82:83]
	s_add_i32 m0, s3, 0xc000
	v_lshlrev_b32_e32 v60, 8, v116
	global_load_lds_dwordx4 v[16:17], off
	v_lshl_add_u64 v[16:17], v[50:51], 0, s[82:83]
	s_add_i32 m0, s3, 0x4000
	v_or_b32_e32 v56, 32, v160
	global_load_lds_dwordx4 v[16:17], off
	v_lshlrev_b32_e32 v16, 4, v116
	v_and_b32_e32 v61, 0xf0, v16
	v_lshrrev_b32_e32 v60, 4, v116
	v_lshlrev_b32_e32 v60, 11, v60
	v_lshl_add_u32 v60, v160, 4, v60
	v_add_u32_e32 v60, v60, v61
	v_or_b32_e32 v16, 0x80, v160
	v_add_u32_e32 v16, 4096, v60
	v_add_u32_e32 v120, 0, v16
	v_mov_b32_e32 v16, v60
	s_waitcnt vmcnt(2) lgkmcnt(0)
	s_barrier
	v_add_u32_e32 v121, 0, v16
	ds_read_b128 v[52:55], v120 offset:32768
	ds_read_b128 v[16:19], v121 offset:32768
	s_waitcnt vmcnt(2) lgkmcnt(0)
	v_mfma_f32_32x32x16_bf16 v[32:47], v[16:19], v[108:111], v[0:15]
	v_add_u32_e32 v56, 512, v60
	v_add_u32_e32 v123, 0, v56
	ds_read_b128 v[56:59], v123 offset:32768
	v_mfma_f32_32x32x16_bf16 v[16:31], v[52:55], v[108:111], v[0:15]
	v_or_b32_e32 v52, 0xa0, v160
	v_add_u32_e32 v52, 4608, v60
	v_add_u32_e32 v122, 0, v52
	ds_read_b128 v[52:55], v122 offset:32768
	s_waitcnt lgkmcnt(1)
	v_mfma_f32_32x32x16_bf16 v[32:47], v[56:59], v[104:107], v[32:47]
	v_or_b32_e32 v56, 64, v160
	v_add_u32_e32 v56, 1024, v60
	v_add_u32_e32 v125, 0, v56
	ds_read_b128 v[56:59], v125 offset:32768
	s_waitcnt lgkmcnt(1)
	v_mfma_f32_32x32x16_bf16 v[16:31], v[52:55], v[104:107], v[16:31]
	v_or_b32_e32 v52, 0xc0, v160
	v_add_u32_e32 v52, 5120, v60
	v_add_u32_e32 v124, 0, v52
	ds_read_b128 v[52:55], v124 offset:32768
	s_waitcnt lgkmcnt(1)
	v_mfma_f32_32x32x16_bf16 v[32:47], v[56:59], v[100:103], v[32:47]
	v_or_b32_e32 v56, 0x60, v160
	v_add_u32_e32 v56, 1536, v60
	v_add_u32_e32 v127, 0, v56
	ds_read_b128 v[56:59], v127 offset:32768
	s_waitcnt lgkmcnt(1)
	v_mfma_f32_32x32x16_bf16 v[16:31], v[52:55], v[100:103], v[16:31]
	v_or_b32_e32 v52, 0xe0, v160
	v_add_u32_e32 v52, 5632, v60
	v_add_u32_e32 v126, 0, v52
	ds_read_b128 v[52:55], v126 offset:32768
	s_waitcnt lgkmcnt(1)
	v_mfma_f32_32x32x16_bf16 v[32:47], v[56:59], v[96:99], v[32:47]
	s_waitcnt lgkmcnt(0)
	v_mfma_f32_32x32x16_bf16 v[16:31], v[52:55], v[96:99], v[16:31]
	s_nop 9
	v_exp_f32_e32 v80, v32
	v_exp_f32_e32 v81, v33
	v_exp_f32_e32 v82, v34
	v_exp_f32_e32 v83, v35
	v_exp_f32_e32 v92, v36
	v_exp_f32_e32 v128, v37
	v_exp_f32_e32 v129, v38
	v_exp_f32_e32 v130, v39
	v_exp_f32_e32 v131, v40
	v_exp_f32_e32 v132, v41
	v_exp_f32_e32 v133, v42
	v_exp_f32_e32 v134, v43
	v_exp_f32_e32 v135, v44
	v_exp_f32_e32 v136, v45
	v_exp_f32_e32 v137, v46
	v_exp_f32_e32 v138, v47
	s_mov_b64 s[6:7], 0xc000
	v_lshl_add_u64 v[32:33], v[48:49], 0, s[6:7]
	s_add_i32 m0, s3, 0xe000
	v_exp_f32_e32 v139, v16
	global_load_lds_dwordx4 v[32:33], off
	v_lshl_add_u64 v[32:33], v[50:51], 0, s[6:7]
	s_add_i32 m0, s3, 0x6000
	v_add_f32_e32 v16, v80, v81
	global_load_lds_dwordx4 v[32:33], off
	ds_read_b128 v[32:35], v121 offset:40960
	v_add_f32_e32 v16, v82, v16
	s_waitcnt lgkmcnt(0)
	v_mfma_f32_32x32x16_bf16 v[48:63], v[32:35], v[108:111], v[0:15]
	ds_read_b128 v[32:35], v120 offset:40960
	ds_read_b128 v[36:39], v122 offset:40960
	ds_read_b128 v[40:43], v123 offset:40960
	ds_read_b128 v[44:47], v124 offset:40960
	s_cmp_lg_u32 0, -1
	v_add_f32_e32 v16, v83, v16
	s_cselect_b32 s3, 0, 0
	v_exp_f32_e32 v140, v17
	v_exp_f32_e32 v141, v18
	v_exp_f32_e32 v142, v19
	s_waitcnt lgkmcnt(0)
	v_mfma_f32_32x32x16_bf16 v[48:63], v[40:43], v[104:107], v[48:63]
	v_exp_f32_e32 v40, v20
	v_add_f32_e32 v20, v92, v16
	v_add_u32_e32 v16, 0, v119
	v_add_u32_e32 v119, s3, v119
	v_exp_f32_e32 v41, v21
	v_exp_f32_e32 v42, v22
	v_exp_f32_e32 v43, v23
	v_mfma_f32_32x32x16_bf16 v[64:79], v[32:35], v[108:111], v[0:15]
	ds_read_b128 v[32:35], v125 offset:40960
	ds_read_b128 v[88:91], v126 offset:40960
	ds_read_b128 v[84:87], v127 offset:40960
	v_exp_f32_e32 v143, v24
	v_exp_f32_e32 v144, v25
	v_exp_f32_e32 v145, v26
	v_exp_f32_e32 v146, v27
	v_exp_f32_e32 v147, v28
	v_exp_f32_e32 v149, v29
	s_waitcnt lgkmcnt(0)
	v_mfma_f32_32x32x16_bf16 v[48:63], v[32:35], v[100:103], v[48:63]
	v_exp_f32_e32 v150, v30
	v_exp_f32_e32 v151, v31
	v_cvt_pk_bf16_f32 v32, v80, v81
	v_cvt_pk_bf16_f32 v33, v82, v83
	v_cvt_pk_bf16_f32 v34, v92, v128
	v_cvt_pk_bf16_f32 v35, v129, v130
	v_cvt_pk_bf16_f32 v92, v131, v132
	v_mfma_f32_32x32x16_bf16 v[64:79], v[36:39], v[104:107], v[64:79]
	v_cvt_pk_bf16_f32 v93, v133, v134
	v_cvt_pk_bf16_f32 v94, v135, v136
	v_cvt_pk_bf16_f32 v95, v137, v138
	v_cvt_pk_bf16_f32 v80, v139, v140
	v_cvt_pk_bf16_f32 v81, v141, v142
	v_cvt_pk_bf16_f32 v82, v40, v41
	v_cvt_pk_bf16_f32 v83, v42, v43
	v_mfma_f32_32x32x16_bf16 v[48:63], v[84:87], v[96:99], v[48:63]
	v_cvt_pk_bf16_f32 v84, v143, v144
	v_cvt_pk_bf16_f32 v85, v145, v146
	v_cvt_pk_bf16_f32 v86, v147, v149
	v_cvt_pk_bf16_f32 v87, v150, v151
	ds_read_b64_tr_b16 v[16:17], v16
	ds_read_b64_tr_b16 v[18:19], v119 offset:256
	v_add_f32_e32 v20, v128, v20
	v_add_f32_e32 v20, v129, v20
	v_add_f32_e32 v20, v130, v20
	v_add_f32_e32 v36, v131, v20
	s_waitcnt lgkmcnt(0)
	v_mfma_f32_32x32x16_bf16 v[16:31], v[32:35], v[16:19], 0
	s_nop 3
	v_exp_f32_e32 v152, v62
	v_exp_f32_e32 v153, v63
	v_mfma_f32_32x32x16_bf16 v[64:79], v[44:47], v[100:103], v[64:79]
	v_add_f32_e32 v44, v132, v36
	ds_read_b64_tr_b16 v[36:37], v119 offset:2048
	ds_read_b64_tr_b16 v[38:39], v119 offset:2304
	v_add_f32_e32 v44, v133, v44
	v_add_f32_e32 v44, v134, v44
	v_add_f32_e32 v44, v135, v44
	v_add_f32_e32 v44, v136, v44
	v_add_f32_e32 v44, v137, v44
	s_waitcnt lgkmcnt(0)
; #define DMA(t) do { const int t_ = (t) < NT ? (t) : NT - 1; const long off_ = (long)t_ * (KVBLK * LDK); \
;         __builtin_amdgcn_global_load_lds((const unsigned*)(kptr + off_), (LAS unsigned*)(ldsK + SLOT(t)), 16, 0, 0); \
;         __builtin_amdgcn_global_load_lds((const unsigned*)(vptr + off_), (LAS unsigned*)(ldsV + SLOT(t)), 16, 0, 0); } while (0)
; #define WBAR(N) asm volatile("s_waitcnt vmcnt(" #N ") lgkmcnt(0)\n\ts_barrier" ::: "memory")
; #define HALF(PX0, PX1, PY0, PY1, j_, MORE) do { \
;         SBAR(); if (MORE) DMA((j_) + 2); qkt(PX0, PX1, K_lds + SLOT(j_), qr, negm, r32, hi); \
;         finishSM(PY0, PY1, l_reg, pa0, pa1, pa2, pa3); \
;         pv_d0(o, vb0 + SLOT((j_) - 1), pa0, pa1, pa2, pa3); partialSM(PX0); \
;         if (MORE) WBAR(2); else WBAR(0); } while (0)
; __device__ __forceinline__ void attn_body(const bf16* __restrict__ Qb, const bf16* __restrict__ Kh, const bf16* __restrict__ Vh, bf16* __restrict__ Ob, int seq, float m0l2, char* lds, bool pre, bool post) {
;     ...
;     if (!pre) { DMA(0); DMA(1); } DMA(2); WBAR(2);
;     qkt(pA0, pA1, K_lds, qr, negm, r32, hi); partialSM(pA0);
;     int j = 1;
;     for (; j + 4 < NT; j += 2) {
;         HALF(pB0, pB1, pA0, pA1, j, true);
;         HALF(pA0, pA1, pB0, pB1, j + 1, true);
;     }
;     HALF(pB0, pB1, pA0, pA1, j, true);
;     HALF(pA0, pA1, pB0, pB1, j + 1, false);
	v_mfma_f32_32x32x16_bf16 v[16:31], v[92:95], v[36:39], v[16:31]
	ds_read_b64_tr_b16 v[36:37], v119 offset:4096
	ds_read_b64_tr_b16 v[38:39], v119 offset:4352
	v_add_f32_e32 v44, v138, v44
	v_add_f32_e32 v44, v139, v44
	v_add_f32_e32 v44, v140, v44
	v_add_f32_e32 v44, v141, v44
	v_add_f32_e32 v44, v142, v44
	v_add_f32_e32 v40, v40, v44
	s_waitcnt lgkmcnt(0)
	v_mfma_f32_32x32x16_bf16 v[16:31], v[80:83], v[36:39], v[16:31]
	ds_read_b64_tr_b16 v[36:37], v119 offset:6144
	ds_read_b64_tr_b16 v[38:39], v119 offset:6400
	v_add_f32_e32 v40, v41, v40
	v_add_f32_e32 v40, v42, v40
	v_add_f32_e32 v40, v43, v40
	v_add_f32_e32 v40, v143, v40
	v_add_f32_e32 v40, v144, v40
	v_add_f32_e32 v40, v145, v40
	s_waitcnt lgkmcnt(0)
	v_mfma_f32_32x32x16_bf16 v[16:31], v[84:87], v[36:39], v[16:31]
	ds_read_b64_tr_b16 v[36:37], v119 offset:512
	ds_read_b64_tr_b16 v[38:39], v119 offset:768
	v_add_f32_e32 v40, v146, v40
	v_exp_f32_e32 v137, v48
	v_exp_f32_e32 v138, v49
	v_exp_f32_e32 v139, v50
	v_exp_f32_e32 v140, v51
	v_exp_f32_e32 v141, v52
	v_mfma_f32_32x32x16_bf16 v[64:79], v[88:91], v[96:99], v[64:79]
	v_add_f32_e32 v88, v147, v40
	v_add_f32_e32 v128, v149, v88
	ds_read_b64_tr_b16 v[88:89], v119 offset:2560
	ds_read_b64_tr_b16 v[90:91], v119 offset:2816
	v_add_f32_e32 v128, v150, v128
	v_add_f32_e32 v128, v151, v128
	v_add_f32_e32 v136, 0, v128
	ds_read_b64_tr_b16 v[128:129], v119 offset:4608
	s_waitcnt lgkmcnt(0)
	v_mfma_f32_32x32x16_bf16 v[32:47], v[32:35], v[36:39], 0
	v_exp_f32_e32 v142, v53
	v_exp_f32_e32 v143, v54
	v_exp_f32_e32 v144, v55
	v_exp_f32_e32 v145, v56
	v_exp_f32_e32 v146, v57
	v_exp_f32_e32 v147, v58
	v_exp_f32_e32 v149, v59
	v_mfma_f32_32x32x16_bf16 v[32:47], v[92:95], v[88:91], v[32:47]
	ds_read_b64_tr_b16 v[130:131], v119 offset:4864
	ds_read_b64_tr_b16 v[88:89], v119 offset:6656
	ds_read_b64_tr_b16 v[90:91], v119 offset:6912
	s_waitcnt vmcnt(2) lgkmcnt(0)
	s_barrier
	v_exp_f32_e32 v150, v60
	v_exp_f32_e32 v151, v61
	s_waitcnt lgkmcnt(0)
	v_mfma_f32_32x32x16_bf16 v[32:47], v[80:83], v[128:131], v[32:47]
	v_mfma_f32_32x32x16_bf16 v[32:47], v[84:87], v[88:91], v[32:47]
	ds_read_b128 v[128:131], v120 offset:49152
	ds_read_b128 v[48:51], v121 offset:49152
	v_exp_f32_e32 v154, v71
	v_exp_f32_e32 v155, v72
	v_exp_f32_e32 v156, v73
	v_exp_f32_e32 v157, v74
	s_waitcnt lgkmcnt(0)
	v_mfma_f32_32x32x16_bf16 v[80:95], v[48:51], v[108:111], v[0:15]
	v_exp_f32_e32 v158, v75
	v_exp_f32_e32 v159, v76
	v_exp_f32_e32 v162, v77
	v_exp_f32_e32 v163, v78
	v_exp_f32_e32 v79, v79
	v_mfma_f32_32x32x16_bf16 v[48:63], v[128:131], v[108:111], v[0:15]
	ds_read_b128 v[128:131], v122 offset:49152
	ds_read_b128 v[132:135], v123 offset:49152
	s_waitcnt lgkmcnt(0)
	v_mfma_f32_32x32x16_bf16 v[48:63], v[128:131], v[104:107], v[48:63]
	v_mfma_f32_32x32x16_bf16 v[80:95], v[132:135], v[104:107], v[80:95]
	ds_read_b128 v[128:131], v124 offset:49152
	ds_read_b128 v[132:135], v125 offset:49152
	s_waitcnt lgkmcnt(0)
	v_mfma_f32_32x32x16_bf16 v[48:63], v[128:131], v[100:103], v[48:63]
	v_mfma_f32_32x32x16_bf16 v[80:95], v[132:135], v[100:103], v[80:95]
	ds_read_b128 v[128:131], v126 offset:49152
	ds_read_b128 v[132:135], v127 offset:49152
	s_waitcnt lgkmcnt(0)
	v_mfma_f32_32x32x16_bf16 v[48:63], v[128:131], v[96:99], v[48:63]
	v_exp_f32_e32 v129, v64
	v_add_f32_e32 v64, v137, v138
	v_add_f32_e32 v64, v139, v64
	v_add_f32_e32 v64, v140, v64
	v_add_f32_e32 v64, v141, v64
	v_add_f32_e32 v64, v142, v64
	v_add_f32_e32 v64, v143, v64
	v_add_f32_e32 v64, v144, v64
	v_add_f32_e32 v64, v145, v64
	v_add_f32_e32 v64, v146, v64
	v_add_f32_e32 v64, v147, v64
	v_add_f32_e32 v64, v149, v64
	v_add_f32_e32 v64, v150, v64
	v_exp_f32_e32 v130, v65
	v_add_f32_e32 v64, v151, v64
	v_exp_f32_e32 v131, v66
	v_add_f32_e32 v64, v152, v64
	v_mfma_f32_32x32x16_bf16 v[80:95], v[132:135], v[96:99], v[80:95]
	v_exp_f32_e32 v132, v67
	v_add_f32_e32 v64, v153, v64
	v_exp_f32_e32 v133, v68
	v_add_f32_e32 v64, v129, v64
	v_exp_f32_e32 v134, v69
	v_add_f32_e32 v64, v130, v64
	v_exp_f32_e32 v135, v70
	v_add_f32_e32 v64, v131, v64
	v_add_f32_e32 v64, v132, v64
	v_add_f32_e32 v64, v133, v64
	v_add_f32_e32 v64, v134, v64
	v_add_f32_e32 v64, v135, v64
	v_add_f32_e32 v64, v154, v64
	v_add_f32_e32 v64, v155, v64
	v_add_f32_e32 v64, v156, v64
	v_add_f32_e32 v64, v157, v64
	v_add_f32_e32 v64, v158, v64
	v_add_f32_e32 v64, v159, v64
	v_add_f32_e32 v64, v162, v64
	v_add_f32_e32 v64, v163, v64
	v_add_f32_e32 v64, v79, v64
	v_add_f32_e32 v128, v136, v64
	v_cvt_pk_bf16_f32 v64, v137, v138
	v_cvt_pk_bf16_f32 v65, v139, v140
	v_cvt_pk_bf16_f32 v66, v141, v142
	v_cvt_pk_bf16_f32 v67, v143, v144
	v_cvt_pk_bf16_f32 v68, v145, v146
	v_cvt_pk_bf16_f32 v69, v147, v149
	v_cvt_pk_bf16_f32 v70, v150, v151
	v_cvt_pk_bf16_f32 v71, v152, v153
	v_cvt_pk_bf16_f32 v72, v129, v130
	v_cvt_pk_bf16_f32 v73, v131, v132
	v_cvt_pk_bf16_f32 v74, v133, v134
	v_cvt_pk_bf16_f32 v75, v135, v154
	v_cvt_pk_bf16_f32 v76, v155, v156
	v_cvt_pk_bf16_f32 v77, v157, v158
	v_cvt_pk_bf16_f32 v78, v159, v162
	v_cvt_pk_bf16_f32 v79, v163, v79
	ds_read_b64_tr_b16 v[130:131], v119 offset:8192
	ds_read_b64_tr_b16 v[132:133], v119 offset:8448
	ds_read_b64_tr_b16 v[134:135], v119 offset:10240
	ds_read_b64_tr_b16 v[136:137], v119 offset:10496
	ds_read_b64_tr_b16 v[138:139], v119 offset:12288
	ds_read_b64_tr_b16 v[140:141], v119 offset:12544
	ds_read_b64_tr_b16 v[142:143], v119 offset:14336
	ds_read_b64_tr_b16 v[144:145], v119 offset:14592
	s_waitcnt lgkmcnt(0)
	v_mfma_f32_32x32x16_bf16 v[16:31], v[64:67], v[130:133], v[16:31]
	v_exp_f32_e32 v129, v80
	v_exp_f32_e32 v88, v88
	v_exp_f32_e32 v89, v89
	v_exp_f32_e32 v90, v90
	v_exp_f32_e32 v91, v91
	v_exp_f32_e32 v92, v92
	v_exp_f32_e32 v93, v93
	v_mfma_f32_32x32x16_bf16 v[16:31], v[68:71], v[134:137], v[16:31]
	v_exp_f32_e32 v94, v94
	v_exp_f32_e32 v95, v95
	v_mfma_f32_32x32x16_bf16 v[16:31], v[72:75], v[138:141], v[16:31]
	v_mfma_f32_32x32x16_bf16 v[16:31], v[76:79], v[142:145], v[16:31]
	ds_read_b64_tr_b16 v[130:131], v119 offset:8704
	ds_read_b64_tr_b16 v[132:133], v119 offset:8960
	ds_read_b64_tr_b16 v[134:135], v119 offset:10752
	ds_read_b64_tr_b16 v[136:137], v119 offset:11008
	ds_read_b64_tr_b16 v[138:139], v119 offset:12800
	ds_read_b64_tr_b16 v[140:141], v119 offset:13056
	ds_read_b64_tr_b16 v[142:143], v119 offset:14848
	ds_read_b64_tr_b16 v[144:145], v119 offset:15104
	s_waitcnt vmcnt(0) lgkmcnt(0)
	s_barrier
; #define SBAR() __builtin_amdgcn_sched_barrier(0)
; #define PK4(P, BASE, OUT) do { unsigned a0 = cvtpk(P[BASE + 0], P[BASE + 1]), a1 = cvtpk(P[BASE + 2], P[BASE + 3]);   \
;     unsigned b0 = cvtpk(P[BASE + 4], P[BASE + 5]), b1 = cvtpk(P[BASE + 6], P[BASE + 7]);                              \
;     u32x4 w = {a0, a1, b0, b1}; OUT = *reinterpret_cast<bf16x8*>(&w); } while (0)
; __device__ __forceinline__ void finishSM(f32x16& p0, f32x16& p1, float& l_reg, bf16x8& pa0, bf16x8& pa1, bf16x8& pa2, bf16x8& pa3) {
; #pragma unroll
;     for (int r = 0; r < 16; ++r) p1[r] = __builtin_amdgcn_exp2f(p1[r]);
;     float ps = p0[0];
; #pragma unroll
;     for (int r = 1; r < 16; ++r) ps += p0[r];
; #pragma unroll
;     for (int r = 0; r < 16; ++r) ps += p1[r];
;     l_reg += ps;
;     ...
;     PK4(p0, 0, pa0); PK4(p0, 8, pa1); PK4(p1, 0, pa2); PK4(p1, 8, pa3);
; __device__ __forceinline__ void attn_body(const bf16* __restrict__ Qb, const bf16* __restrict__ Kh, const bf16* __restrict__ Vh, bf16* __restrict__ Ob, int seq, float m0l2, char* lds, bool pre, bool post) {
;     ...
;     SBAR(); qkt(pB0, pB1, K_lds + SLOT(NT - 1), qr, negm, r32, hi);
;     finishSM(pA0, pA1, l_reg, pa0, pa1, pa2, pa3); SBAR();
;     pv_d0(o, vb0 + SLOT(NT - 2), pa0, pa1, pa2, pa3); partialSM(pB0);
	s_waitcnt lgkmcnt(0)
	v_mfma_f32_32x32x16_bf16 v[32:47], v[64:67], v[130:133], v[32:47]
	v_exp_f32_e32 v130, v81
	v_exp_f32_e32 v131, v82
	v_exp_f32_e32 v132, v83
	v_exp_f32_e32 v133, v84
	v_mfma_f32_32x32x16_bf16 v[32:47], v[68:71], v[134:137], v[32:47]
	v_exp_f32_e32 v134, v85
	v_exp_f32_e32 v135, v86
	v_exp_f32_e32 v136, v87
	v_mfma_f32_32x32x16_bf16 v[32:47], v[72:75], v[138:141], v[32:47]
	v_mfma_f32_32x32x16_bf16 v[32:47], v[76:79], v[142:145], v[32:47]
	ds_read_b128 v[80:83], v120 offset:57344
	ds_read_b128 v[84:87], v121 offset:57344
	v_exp_f32_e32 v63, v63
	s_waitcnt lgkmcnt(0)
	v_mfma_f32_32x32x16_bf16 v[64:79], v[84:87], v[108:111], v[0:15]
	v_mfma_f32_32x32x16_bf16 v[0:15], v[80:83], v[108:111], v[0:15]
	ds_read_b128 v[80:83], v122 offset:57344
	ds_read_b128 v[84:87], v123 offset:57344
	s_waitcnt lgkmcnt(0)
	v_mfma_f32_32x32x16_bf16 v[0:15], v[80:83], v[104:107], v[0:15]
	v_mfma_f32_32x32x16_bf16 v[64:79], v[84:87], v[104:107], v[64:79]
	ds_read_b128 v[80:83], v124 offset:57344
	ds_read_b128 v[84:87], v125 offset:57344
	s_waitcnt lgkmcnt(0)
	v_mfma_f32_32x32x16_bf16 v[0:15], v[80:83], v[100:103], v[0:15]
	v_mfma_f32_32x32x16_bf16 v[64:79], v[84:87], v[100:103], v[64:79]
	ds_read_b128 v[80:83], v126 offset:57344
	ds_read_b128 v[84:87], v127 offset:57344
	v_exp_f32_e32 v100, v60
	v_exp_f32_e32 v101, v61
	v_exp_f32_e32 v102, v62
	s_waitcnt lgkmcnt(0)
	v_mfma_f32_32x32x16_bf16 v[0:15], v[80:83], v[96:99], v[0:15]
	v_exp_f32_e32 v80, v48
	v_add_f32_e32 v48, v129, v130
	v_add_f32_e32 v48, v131, v48
	v_add_f32_e32 v48, v132, v48
	v_add_f32_e32 v48, v133, v48
	v_add_f32_e32 v48, v134, v48
	v_add_f32_e32 v48, v135, v48
	v_add_f32_e32 v48, v136, v48
	v_add_f32_e32 v48, v88, v48
	v_add_f32_e32 v48, v89, v48
	v_add_f32_e32 v48, v90, v48
	v_add_f32_e32 v48, v91, v48
	v_add_f32_e32 v48, v92, v48
	v_exp_f32_e32 v81, v49
	v_add_f32_e32 v48, v93, v48
	v_exp_f32_e32 v82, v50
	v_add_f32_e32 v48, v94, v48
	v_exp_f32_e32 v83, v51
	v_add_f32_e32 v48, v95, v48
	v_mfma_f32_32x32x16_bf16 v[64:79], v[84:87], v[96:99], v[64:79]
	v_exp_f32_e32 v84, v52
	v_add_f32_e32 v48, v80, v48
	v_exp_f32_e32 v85, v53
	v_add_f32_e32 v48, v81, v48
	v_exp_f32_e32 v86, v54
	v_add_f32_e32 v48, v82, v48
	v_exp_f32_e32 v87, v55
	v_add_f32_e32 v48, v83, v48
	v_exp_f32_e32 v96, v56
	v_add_f32_e32 v48, v84, v48
	v_exp_f32_e32 v97, v57
	v_add_f32_e32 v48, v85, v48
	v_exp_f32_e32 v98, v58
	v_add_f32_e32 v48, v86, v48
	v_exp_f32_e32 v99, v59
	v_add_f32_e32 v48, v87, v48
	v_add_f32_e32 v48, v96, v48
	v_add_f32_e32 v48, v97, v48
	v_add_f32_e32 v48, v98, v48
	v_add_f32_e32 v48, v99, v48
	v_add_f32_e32 v48, v100, v48
	v_add_f32_e32 v48, v101, v48
	v_add_f32_e32 v48, v102, v48
	v_add_f32_e32 v48, v63, v48
	v_add_f32_e32 v103, v128, v48
	v_cvt_pk_bf16_f32 v48, v129, v130
	v_cvt_pk_bf16_f32 v49, v131, v132
	v_cvt_pk_bf16_f32 v50, v133, v134
	v_cvt_pk_bf16_f32 v51, v135, v136
	v_cvt_pk_bf16_f32 v52, v88, v89
	v_cvt_pk_bf16_f32 v53, v90, v91
	v_cvt_pk_bf16_f32 v54, v92, v93
	v_cvt_pk_bf16_f32 v55, v94, v95
	v_cvt_pk_bf16_f32 v56, v80, v81
	v_cvt_pk_bf16_f32 v57, v82, v83
	v_cvt_pk_bf16_f32 v58, v84, v85
	v_cvt_pk_bf16_f32 v59, v86, v87
	v_cvt_pk_bf16_f32 v60, v96, v97
	v_cvt_pk_bf16_f32 v61, v98, v99
	v_cvt_pk_bf16_f32 v62, v100, v101
	v_cvt_pk_bf16_f32 v63, v102, v63
	ds_read_b64_tr_b16 v[80:81], v119 offset:16384
	ds_read_b64_tr_b16 v[82:83], v119 offset:16640
	ds_read_b64_tr_b16 v[84:85], v119 offset:18432
	ds_read_b64_tr_b16 v[86:87], v119 offset:18688
	ds_read_b64_tr_b16 v[88:89], v119 offset:20480
	ds_read_b64_tr_b16 v[90:91], v119 offset:20736
	ds_read_b64_tr_b16 v[92:93], v119 offset:22528
	ds_read_b64_tr_b16 v[94:95], v119 offset:22784
	s_waitcnt lgkmcnt(0)
	v_mfma_f32_32x32x16_bf16 v[16:31], v[48:51], v[80:83], v[16:31]
	v_exp_f32_e32 v1, v1
	v_exp_f32_e32 v14, v14
	v_exp_f32_e32 v15, v15
	v_mfma_f32_32x32x16_bf16 v[16:31], v[52:55], v[84:87], v[16:31]
	v_mfma_f32_32x32x16_bf16 v[16:31], v[56:59], v[88:91], v[16:31]
	v_mfma_f32_32x32x16_bf16 v[16:31], v[60:63], v[92:95], v[16:31]
	ds_read_b64_tr_b16 v[80:81], v119 offset:16896
	ds_read_b64_tr_b16 v[82:83], v119 offset:17152
	ds_read_b64_tr_b16 v[84:85], v119 offset:18944
	ds_read_b64_tr_b16 v[86:87], v119 offset:19200
	ds_read_b64_tr_b16 v[88:89], v119 offset:20992
	ds_read_b64_tr_b16 v[90:91], v119 offset:21248
	ds_read_b64_tr_b16 v[92:93], v119 offset:23040
	ds_read_b64_tr_b16 v[94:95], v119 offset:23296
	s_waitcnt lgkmcnt(0)
; #define SBAR() __builtin_amdgcn_sched_barrier(0)
; __device__ __forceinline__ int crow(int r, int hi) { return (r & 3) + 8 * (r >> 2) + 4 * hi; }
; __device__ __forceinline__ void attn_body(const bf16* __restrict__ Qb, const bf16* __restrict__ Kh, const bf16* __restrict__ Vh, bf16* __restrict__ Ob, int seq, float m0l2, char* lds, bool pre, bool post) {
;     ...
;     finishSM(pA0, pA1, l_reg, pa0, pa1, pa2, pa3); SBAR();
;     pv_d0(o, vb0 + SLOT(NT - 2), pa0, pa1, pa2, pa3); partialSM(pB0);
;     finishSM(pB0, pB1, l_reg, pa0, pa1, pa2, pa3); SBAR();
;     pv_d0(o, vb0 + SLOT(NT - 1), pa0, pa1, pa2, pa3);
;     { auto rr = __builtin_amdgcn_permlane32_swap(__float_as_uint(l_reg), __float_as_uint(l_reg), false, false); l_reg = __uint_as_float(rr[0]) + __uint_as_float(rr[1]); }
;     if (hi == 0) li_l[r32] = l_reg; asm volatile("s_waitcnt lgkmcnt(0)" ::: "memory");
;     float rli[16];
; #pragma unroll
;     for (int r = 0; r < 16; ++r) rli[r] = __builtin_amdgcn_rcpf(li_l[crow(r, hi)]);
	v_mfma_f32_32x32x16_bf16 v[32:47], v[48:51], v[80:83], v[32:47]
	v_exp_f32_e32 v48, v64
	v_exp_f32_e32 v49, v65
	v_exp_f32_e32 v50, v66
	v_exp_f32_e32 v51, v67
	v_exp_f32_e32 v64, v0
	v_add_f32_e32 v0, v48, v49
	v_add_f32_e32 v0, v50, v0
	v_mfma_f32_32x32x16_bf16 v[32:47], v[52:55], v[84:87], v[32:47]
	v_exp_f32_e32 v52, v68
	v_exp_f32_e32 v53, v69
	v_exp_f32_e32 v54, v70
	v_exp_f32_e32 v55, v71
	v_add_f32_e32 v0, v51, v0
	v_add_f32_e32 v0, v52, v0
	v_add_f32_e32 v0, v53, v0
	v_mfma_f32_32x32x16_bf16 v[32:47], v[56:59], v[88:91], v[32:47]
	v_exp_f32_e32 v56, v72
	v_exp_f32_e32 v57, v73
	v_exp_f32_e32 v58, v74
	v_add_f32_e32 v0, v54, v0
	v_exp_f32_e32 v59, v75
	v_add_f32_e32 v0, v55, v0
	v_add_f32_e32 v0, v56, v0
	v_mfma_f32_32x32x16_bf16 v[32:47], v[60:63], v[92:95], v[32:47]
	v_exp_f32_e32 v60, v76
	v_exp_f32_e32 v61, v77
	v_add_f32_e32 v0, v57, v0
	v_exp_f32_e32 v62, v78
	v_add_f32_e32 v0, v58, v0
	v_exp_f32_e32 v63, v79
	v_add_f32_e32 v0, v59, v0
	v_add_f32_e32 v0, v60, v0
	v_add_f32_e32 v0, v61, v0
	v_exp_f32_e32 v65, v2
	v_add_f32_e32 v0, v62, v0
	v_exp_f32_e32 v66, v3
	v_add_f32_e32 v0, v63, v0
	v_exp_f32_e32 v67, v4
	v_add_f32_e32 v0, v64, v0
	v_exp_f32_e32 v68, v5
	v_add_f32_e32 v0, v1, v0
	v_exp_f32_e32 v69, v6
	v_add_f32_e32 v0, v65, v0
	v_exp_f32_e32 v70, v7
	v_add_f32_e32 v0, v66, v0
	v_exp_f32_e32 v71, v8
	v_add_f32_e32 v0, v67, v0
	v_exp_f32_e32 v72, v9
	v_add_f32_e32 v0, v68, v0
	v_exp_f32_e32 v73, v10
	v_add_f32_e32 v0, v69, v0
	v_exp_f32_e32 v74, v11
	v_add_f32_e32 v0, v70, v0
	v_exp_f32_e32 v75, v12
	v_add_f32_e32 v0, v71, v0
	v_exp_f32_e32 v76, v13
	v_add_f32_e32 v0, v72, v0
	v_add_f32_e32 v0, v73, v0
	v_add_f32_e32 v0, v74, v0
	v_add_f32_e32 v0, v75, v0
	v_add_f32_e32 v0, v76, v0
	v_add_f32_e32 v0, v14, v0
	v_add_f32_e32 v0, v15, v0
	v_add_f32_e32 v0, v103, v0
	v_cvt_pk_bf16_f32 v2, v48, v49
	v_cvt_pk_bf16_f32 v3, v50, v51
	v_cvt_pk_bf16_f32 v4, v52, v53
	v_cvt_pk_bf16_f32 v5, v54, v55
	v_cvt_pk_bf16_f32 v6, v56, v57
	v_cvt_pk_bf16_f32 v7, v58, v59
	v_cvt_pk_bf16_f32 v8, v60, v61
	v_cvt_pk_bf16_f32 v9, v62, v63
	v_cvt_pk_bf16_f32 v10, v64, v1
	v_cvt_pk_bf16_f32 v11, v65, v66
	v_cvt_pk_bf16_f32 v12, v67, v68
	v_cvt_pk_bf16_f32 v13, v69, v70
	v_cvt_pk_bf16_f32 v48, v71, v72
	v_cvt_pk_bf16_f32 v49, v73, v74
	v_cvt_pk_bf16_f32 v50, v75, v76
	v_cvt_pk_bf16_f32 v51, v14, v15
	ds_read_b64_tr_b16 v[52:53], v119 offset:24576
	ds_read_b64_tr_b16 v[54:55], v119 offset:24832
	v_mov_b32_e32 v1, v0
	s_nop 1
	v_permlane32_swap_b32_e32 v0, v1
	v_cmp_gt_u32_e32 vcc, 32, v115
	s_waitcnt lgkmcnt(0)
	v_mfma_f32_32x32x16_bf16 v[16:31], v[2:5], v[52:55], v[16:31]
	ds_read_b64_tr_b16 v[52:53], v119 offset:26624
	ds_read_b64_tr_b16 v[54:55], v119 offset:26880
	s_waitcnt lgkmcnt(0)
	v_mfma_f32_32x32x16_bf16 v[16:31], v[6:9], v[52:55], v[16:31]
	ds_read_b64_tr_b16 v[52:53], v119 offset:28672
	ds_read_b64_tr_b16 v[54:55], v119 offset:28928
	s_waitcnt lgkmcnt(0)
	v_mfma_f32_32x32x16_bf16 v[16:31], v[10:13], v[52:55], v[16:31]
	ds_read_b64_tr_b16 v[52:53], v119 offset:30720
	ds_read_b64_tr_b16 v[54:55], v119 offset:30976
	s_waitcnt lgkmcnt(0)
	v_mfma_f32_32x32x16_bf16 v[16:31], v[48:51], v[52:55], v[16:31]
	ds_read_b64_tr_b16 v[52:53], v119 offset:25088
	ds_read_b64_tr_b16 v[54:55], v119 offset:25344
	s_waitcnt lgkmcnt(0)
	v_mfma_f32_32x32x16_bf16 v[32:47], v[2:5], v[52:55], v[32:47]
	ds_read_b64_tr_b16 v[2:3], v119 offset:27136
	ds_read_b64_tr_b16 v[4:5], v119 offset:27392
	s_waitcnt lgkmcnt(0)
	v_mfma_f32_32x32x16_bf16 v[32:47], v[6:9], v[2:5], v[32:47]
	ds_read_b64_tr_b16 v[2:3], v119 offset:29184
	ds_read_b64_tr_b16 v[4:5], v119 offset:29440
	s_waitcnt lgkmcnt(0)
	v_mfma_f32_32x32x16_bf16 v[32:47], v[10:13], v[2:5], v[32:47]
	ds_read_b64_tr_b16 v[2:3], v119 offset:31232
	ds_read_b64_tr_b16 v[4:5], v119 offset:31488
	s_waitcnt lgkmcnt(0)
	v_mfma_f32_32x32x16_bf16 v[32:47], v[48:51], v[2:5], v[32:47]
	s_and_saveexec_b64 s[6:7], vcc
	v_add_f32_e32 v0, v0, v1
	v_lshl_add_u32 v1, v116, 2, v113
	ds_write_b32 v1, v0
	s_or_b64 exec, exec, s[6:7]
	s_waitcnt lgkmcnt(0)
	v_add_u32_e32 v8, v113, v160
	ds_read_b128 v[0:3], v8
	ds_read_b128 v[4:7], v8 offset:32
	v_readlane_b32 s3, v254, 7
	s_add_u32 s3, s16, s3
	s_addc_u32 s7, s17, 0
	s_waitcnt lgkmcnt(0)
; __device__ __forceinline__ unsigned f2bf(float f) { unsigned u = __builtin_bit_cast(unsigned, f); return (u + 0x7fffu + ((u >> 16) & 1u)) >> 16; }
; __device__ __forceinline__ int crow(int r, int hi) { return (r & 3) + 8 * (r >> 2) + 4 * hi; }
; __device__ __forceinline__ void attn_body(const bf16* __restrict__ Qb, const bf16* __restrict__ Kh, const bf16* __restrict__ Vh, bf16* __restrict__ Ob, int seq, float m0l2, char* lds, bool pre, bool post) {
;     ...
;     float rli[16];
; #pragma unroll
;     for (int r = 0; r < 16; ++r) rli[r] = __builtin_amdgcn_rcpf(li_l[crow(r, hi)]);
;     bf16* Ow = Ob + (long)(wid * QBLK) * LDO;
;     {
;         bf16* stg = (bf16*)(lds + OFF_OST) + wid * 2048;
; #pragma unroll
;         for (int r = 0; r < 16; ++r) { const int orow = crow(r, hi);
; #pragma unroll
;             for (int d0 = 0; d0 < 2; ++d0) stg[orow * 64 + d0 * 32 + r32] = (bf16)f2bf(o[d0][r] * rli[r]); }
;         asm volatile("s_waitcnt lgkmcnt(0)" ::: "memory");
; #pragma unroll
;         for (int i = 0; i < 4; ++i) { const int row = i * 8 + (lane >> 3), ch = lane & 7; const u32x4 v = *(const u32x4*)(stg + row * 64 + ch * 8); *(u32x4*)(Ow + (long)row * LDO + ch * 8) = v; }
;     }
;     asm volatile("s_waitcnt vmcnt(0)" ::: "memory");
;     __syncthreads();
	v_rcp_f32_e32 v9, v0
	v_readlane_b32 s8, v254, 61
	s_add_u32 s6, s3, s8
	v_readlane_b32 s3, v255, 1
	v_lshlrev_b32_e32 v51, 9, v118
	v_lshlrev_b32_e32 v52, 1, v116
	v_lshl_add_u32 v50, v117, 12, s3
	v_mul_f32_e32 v16, v16, v9
	v_rcp_f32_e32 v10, v1
	v_add3_u32 v51, v50, v51, v52
	v_bfe_u32 v52, v16, 16, 1
	v_add3_u32 v16, v16, v52, s56
	v_mul_f32_e32 v9, v32, v9
	ds_write_b16_d16_hi v51, v16
	v_bfe_u32 v16, v9, 16, 1
	v_add3_u32 v9, v9, v16, s56
	ds_write_b16_d16_hi v51, v9 offset:64
	v_mul_f32_e32 v9, v17, v10
	v_bfe_u32 v16, v9, 16, 1
	v_rcp_f32_e32 v11, v2
	v_add3_u32 v9, v9, v16, s56
	ds_write_b16_d16_hi v51, v9 offset:128
	v_mul_f32_e32 v9, v33, v10
	v_bfe_u32 v10, v9, 16, 1
	v_add3_u32 v9, v9, v10, s56
	ds_write_b16_d16_hi v51, v9 offset:192
	v_mul_f32_e32 v9, v18, v11
	v_bfe_u32 v10, v9, 16, 1
	v_rcp_f32_e32 v12, v3
	v_add3_u32 v9, v9, v10, s56
	ds_write_b16_d16_hi v51, v9 offset:256
	v_mul_f32_e32 v9, v34, v11
	v_bfe_u32 v10, v9, 16, 1
	v_add3_u32 v9, v9, v10, s56
	ds_write_b16_d16_hi v51, v9 offset:320
	v_mul_f32_e32 v9, v19, v12
	v_bfe_u32 v10, v9, 16, 1
	v_rcp_f32_e32 v13, v4
	v_add3_u32 v9, v9, v10, s56
	ds_write_b16_d16_hi v51, v9 offset:384
	v_mul_f32_e32 v9, v35, v12
	v_bfe_u32 v10, v9, 16, 1
	v_add3_u32 v9, v9, v10, s56
	ds_write_b16_d16_hi v51, v9 offset:448
	v_mul_f32_e32 v9, v20, v13
	v_bfe_u32 v10, v9, 16, 1
	v_rcp_f32_e32 v14, v5
	v_add3_u32 v9, v9, v10, s56
	ds_write_b16_d16_hi v51, v9 offset:1024
	v_mul_f32_e32 v9, v36, v13
	v_bfe_u32 v10, v9, 16, 1
	v_add3_u32 v9, v9, v10, s56
	ds_write_b16_d16_hi v51, v9 offset:1088
	v_mul_f32_e32 v9, v21, v14
	v_bfe_u32 v10, v9, 16, 1
	v_rcp_f32_e32 v15, v6
	v_add3_u32 v9, v9, v10, s56
	ds_write_b16_d16_hi v51, v9 offset:1152
	v_mul_f32_e32 v9, v37, v14
	v_bfe_u32 v10, v9, 16, 1
	v_add3_u32 v9, v9, v10, s56
	ds_write_b16_d16_hi v51, v9 offset:1216
	v_mul_f32_e32 v9, v22, v15
	v_bfe_u32 v10, v9, 16, 1
	v_rcp_f32_e32 v48, v7
	v_add3_u32 v9, v9, v10, s56
	ds_read_b128 v[0:3], v8 offset:64
	ds_read_b128 v[4:7], v8 offset:96
	ds_write_b16_d16_hi v51, v9 offset:1280
	v_mul_f32_e32 v9, v38, v15
	v_bfe_u32 v10, v9, 16, 1
	v_add3_u32 v9, v9, v10, s56
	ds_write_b16_d16_hi v51, v9 offset:1344
	v_mul_f32_e32 v9, v23, v48
	v_bfe_u32 v10, v9, 16, 1
	s_waitcnt lgkmcnt(0)
	v_rcp_f32_e32 v8, v0
	v_add3_u32 v9, v9, v10, s56
	ds_write_b16_d16_hi v51, v9 offset:1408
	v_mul_f32_e32 v9, v39, v48
	v_bfe_u32 v10, v9, 16, 1
	v_add3_u32 v9, v9, v10, s56
	ds_write_b16_d16_hi v51, v9 offset:1472
	v_mul_f32_e32 v9, v24, v8
	v_rcp_f32_e32 v49, v1
	v_bfe_u32 v10, v9, 16, 1
	v_add3_u32 v9, v9, v10, s56
	v_mul_f32_e32 v8, v40, v8
	ds_write_b16_d16_hi v51, v9 offset:2048
	v_bfe_u32 v9, v8, 16, 1
	v_add3_u32 v8, v8, v9, s56
	ds_write_b16_d16_hi v51, v8 offset:2112
	v_mul_f32_e32 v8, v25, v49
	v_bfe_u32 v9, v8, 16, 1
	v_rcp_f32_e32 v2, v2
	v_add3_u32 v8, v8, v9, s56
	ds_write_b16_d16_hi v51, v8 offset:2176
	v_mul_f32_e32 v8, v41, v49
	v_bfe_u32 v9, v8, 16, 1
	v_add3_u32 v8, v8, v9, s56
	ds_write_b16_d16_hi v51, v8 offset:2240
	v_mul_f32_e32 v8, v26, v2
	v_rcp_f32_e32 v3, v3
	v_bfe_u32 v9, v8, 16, 1
	v_add3_u32 v8, v8, v9, s56
	v_mul_f32_e32 v2, v42, v2
	ds_write_b16_d16_hi v51, v8 offset:2304
	v_bfe_u32 v8, v2, 16, 1
	v_add3_u32 v2, v2, v8, s56
	ds_write_b16_d16_hi v51, v2 offset:2368
	v_mul_f32_e32 v2, v27, v3
	v_bfe_u32 v8, v2, 16, 1
	v_rcp_f32_e32 v4, v4
	v_add3_u32 v2, v2, v8, s56
	ds_write_b16_d16_hi v51, v2 offset:2432
	v_mul_f32_e32 v2, v43, v3
	v_bfe_u32 v3, v2, 16, 1
	v_add3_u32 v2, v2, v3, s56
	ds_write_b16_d16_hi v51, v2 offset:2496
	v_mul_f32_e32 v2, v28, v4
	v_bfe_u32 v3, v2, 16, 1
	v_rcp_f32_e32 v5, v5
	v_add3_u32 v2, v2, v3, s56
	ds_write_b16_d16_hi v51, v2 offset:3072
	v_mul_f32_e32 v2, v44, v4
	v_bfe_u32 v3, v2, 16, 1
	v_add3_u32 v2, v2, v3, s56
	ds_write_b16_d16_hi v51, v2 offset:3136
	v_mul_f32_e32 v2, v29, v5
	v_bfe_u32 v3, v2, 16, 1
	v_rcp_f32_e32 v6, v6
	v_add3_u32 v2, v2, v3, s56
	ds_write_b16_d16_hi v51, v2 offset:3200
	v_mul_f32_e32 v2, v45, v5
	v_bfe_u32 v3, v2, 16, 1
	v_add3_u32 v2, v2, v3, s56
	ds_write_b16_d16_hi v51, v2 offset:3264
	v_mul_f32_e32 v2, v30, v6
	v_bfe_u32 v3, v2, 16, 1
	v_rcp_f32_e32 v7, v7
	v_add3_u32 v2, v2, v3, s56
	ds_write_b16_d16_hi v51, v2 offset:3328
	v_mul_f32_e32 v2, v46, v6
	v_bfe_u32 v3, v2, 16, 1
	v_add3_u32 v2, v2, v3, s56
	ds_write_b16_d16_hi v51, v2 offset:3392
	v_mul_f32_e32 v2, v31, v7
	v_bfe_u32 v3, v2, 16, 1
	v_add3_u32 v2, v2, v3, s56
	ds_write_b16_d16_hi v51, v2 offset:3456
	v_mul_f32_e32 v2, v47, v7
	v_bfe_u32 v3, v2, 16, 1
	v_add3_u32 v2, v2, v3, s56
	v_readlane_b32 s9, v254, 62
	v_ashrrev_i32_e32 v113, 31, v112
	ds_write_b16_d16_hi v51, v2 offset:3520
	v_lshlrev_b32_e32 v2, 4, v114
	s_addc_u32 s7, s7, s9
	v_lshlrev_b64 v[0:1], 11, v[112:113]
	v_and_b32_e32 v160, 0x70, v2
	v_lshl_add_u64 v[0:1], s[6:7], 0, v[0:1]
	v_lshrrev_b32_e32 v12, 3, v115
	v_add_u32_e32 v13, v50, v160
	s_waitcnt lgkmcnt(0)
	v_lshl_add_u64 v[8:9], v[0:1], 0, v[160:161]
	v_lshl_add_u32 v0, v12, 7, v13
	v_or_b32_e32 v14, 8, v12
	ds_read_b128 v[0:3], v0
	v_lshl_add_u32 v4, v14, 7, v13
	ds_read_b128 v[4:7], v4
	v_lshlrev_b32_e32 v160, 11, v12
	v_lshl_add_u64 v[10:11], v[8:9], 0, v[160:161]
	v_lshlrev_b32_e32 v160, 11, v14
	s_waitcnt lgkmcnt(0)
	global_store_dwordx4 v[10:11], v[0:3], off
	s_nop 1
	v_lshl_add_u64 v[0:1], v[8:9], 0, v[160:161]
	global_store_dwordx4 v[0:1], v[4:7], off
	s_nop 1
	v_or_b32_e32 v4, 16, v12
	v_lshl_add_u32 v0, v4, 7, v13
	v_or_b32_e32 v12, 24, v12
	ds_read_b128 v[0:3], v0
	v_lshlrev_b32_e32 v160, 11, v4
	v_lshl_add_u32 v4, v12, 7, v13
	ds_read_b128 v[4:7], v4
	v_lshl_add_u64 v[10:11], v[8:9], 0, v[160:161]
	v_lshlrev_b32_e32 v160, 11, v12
	s_waitcnt lgkmcnt(0)
	global_store_dwordx4 v[10:11], v[0:3], off
	s_nop 1
	v_lshl_add_u64 v[0:1], v[8:9], 0, v[160:161]
	global_store_dwordx4 v[0:1], v[4:7], off
	s_waitcnt vmcnt(4)
	s_waitcnt vmcnt(4)
	s_barrier
